# k22 (early ssq loads) without the vmcnt(0) drain in the SwiGLU epilogue: the next tile's in-flight LDS-DMA no longer stalls the epilogue; K-loop counted waits still cover every transfer
# speedup vs baseline: 1.0042x; 1.0012x over previous
; __device__ __forceinline__ unsigned cvtpk(float lo, float hi) { f32x2_t v = {lo, hi}; bf16x2_t b = __builtin_convertvector(v, bf16x2_t); return __builtin_bit_cast(unsigned, b); }
; __device__ __forceinline__ float ssq_sum(const float* p) {
;     const f32x4 a = *(const f32x4*)p, b = *(const f32x4*)(p + 4), c = *(const f32x4*)(p + 8), d = *(const f32x4*)(p + 12);
;     return (((a[0] + a[1]) + (a[2] + a[3])) + ((b[0] + b[1]) + (b[2] + b[3]))) + (((c[0] + c[1]) + (c[2] + c[3])) + ((d[0] + d[1]) + (d[2] + d[3])));
;     __device__ __forceinline__ void operator()(const f32x4 (&acc)[2][2][4][2], const Unit& u, int wr, int wc, int fr, int fq) const {
;         const int row0 = u.pm * BM + wr * 64 + fr, col0 = u.pn * 128 + wc * 32 + 8 * fq;
; #pragma unroll
;         for (int ai = 0; ai < 2; ++ai)
; #pragma unroll
;             for (int m = 0; m < 4; ++m) {
;                 const int row = row0 + ai * HALF + m * 16;
;                 const float rs = 1.0f / sqrtf(ssq_sum(ssq + (size_t)row * 16) * (1.0f / DM) + EPS);
;                 float hv[8];
; #pragma unroll
;                 for (int n = 0; n < 2; ++n)
; #pragma unroll
;                     for (int e = 0; e < 4; ++e) {
;                         const float gg = acc[ai][0][m][n][e] * rs, uu = acc[ai][1][m][n][e] * rs;
;                         const float den = 1.0f + __builtin_amdgcn_exp2f(-gg * LOG2E);
;                         hv[n * 4 + e] = gg * uu * __builtin_amdgcn_rcpf(den);
;                     }
;                 u32x4 w; w.x = cvtpk(hv[0], hv[1]); w.y = cvtpk(hv[2], hv[3]); w.z = cvtpk(hv[4], hv[5]); w.w = cvtpk(hv[6], hv[7]);
;                 *(u32x4*)(H + (size_t)row * DFF + col0) = w;
.LBB0_244:
	v_readlane_b32 s9, v254, 7
	v_mbcnt_lo_u32_b32 v144, -1, 0
	v_mbcnt_hi_u32_b32 v144, -1, v144
	v_lshrrev_b32_e32 v145, 1, v144
	v_lshl_add_u32 v145, s9, 5, v145
	v_and_b32_e32 v146, 1, v144
	v_lshl_add_u32 v148, s8, 8, v152
	v_mov_b64_e32 v[146:147], s[16:17]
	v_mad_i64_i32 v[176:177], s[8:9], v148, s56, v[146:147]
	v_lshl_or_b32 v150, s2, 7, v154
	v_mov_b32_e32 v151, 0
	v_lshlrev_b64 v[150:151], 1, v[150:151]
	v_lshl_add_u64 v[176:177], v[176:177], 0, v[150:151]
	v_lshlrev_b32_e32 v145, 3, v145
	v_add_u32_e32 v145, 0x20100, v145
	v_lshlrev_b32_e32 v146, 3, v152
	v_add_u32_e32 v146, 0x20100, v146
	s_mov_b32 s9, 0
	v_pk_add_f32 v[160:161], v[230:231], v[232:233]
	v_pk_add_f32 v[164:165], v[234:235], v[236:237]
	v_pk_add_f32 v[160:161], v[160:161], v[164:165]
	v_add_f32_e32 v160, v160, v161
	s_nop 1
	v_add_f32_dpp v160, v160, v160 quad_perm:[1,0,3,2] row_mask:0xf bank_mask:0xf
	v_fmamk_f32 v160, v160, 0x3a800000, v158
	v_rsq_f32_e32 v161, v160
	s_nop 0
	v_mul_f32_e32 v161, 0xbfb8aa3b, v161
	ds_write_b64 v145, v[160:161]
	s_waitcnt lgkmcnt(0)
	s_barrier
	ds_read_b64 v[160:161], v146 offset:0
	ds_read_b64 v[162:163], v146 offset:128
	ds_read_b64 v[164:165], v146 offset:256
	ds_read_b64 v[166:167], v146 offset:384
	ds_read_b64 v[168:169], v146 offset:1024
	ds_read_b64 v[170:171], v146 offset:1152
	ds_read_b64 v[172:173], v146 offset:1280
	ds_read_b64 v[174:175], v146 offset:1408
	v_pk_mul_f32 v[116:117], v[124:125], v[116:117]
	v_pk_mul_f32 v[118:119], v[126:127], v[118:119]
	v_pk_mul_f32 v[112:113], v[120:121], v[112:113]
	v_pk_mul_f32 v[114:115], v[122:123], v[114:115]
	s_waitcnt lgkmcnt(7)
	v_mov_b32_e32 v150, v161
	v_pk_mul_f32 v[124:125], v[124:125], v[150:151] op_sel_hi:[1,0]
	v_pk_mul_f32 v[126:127], v[126:127], v[150:151] op_sel_hi:[1,0]
	v_pk_mul_f32 v[120:121], v[120:121], v[150:151] op_sel_hi:[1,0]
	v_pk_mul_f32 v[122:123], v[122:123], v[150:151] op_sel_hi:[1,0]
	v_exp_f32_e32 v124, v124
	v_exp_f32_e32 v125, v125
	v_exp_f32_e32 v126, v126
	v_exp_f32_e32 v127, v127
	v_exp_f32_e32 v120, v120
	v_exp_f32_e32 v121, v121
	v_exp_f32_e32 v122, v122
	v_exp_f32_e32 v123, v123
	v_fma_f32 v124, v124, v160, v160
	v_fma_f32 v125, v125, v160, v160
	v_fma_f32 v126, v126, v160, v160
	v_fma_f32 v127, v127, v160, v160
	v_fma_f32 v120, v120, v160, v160
	v_fma_f32 v121, v121, v160, v160
	v_fma_f32 v122, v122, v160, v160
	v_fma_f32 v123, v123, v160, v160
	v_rcp_f32_e32 v124, v124
	v_rcp_f32_e32 v125, v125
	v_rcp_f32_e32 v126, v126
	v_rcp_f32_e32 v127, v127
	v_rcp_f32_e32 v120, v120
	v_rcp_f32_e32 v121, v121
	v_rcp_f32_e32 v122, v122
	v_rcp_f32_e32 v123, v123
	v_pk_mul_f32 v[116:117], v[116:117], v[124:125]
	v_pk_mul_f32 v[118:119], v[118:119], v[126:127]
	v_pk_mul_f32 v[112:113], v[112:113], v[120:121]
	v_pk_mul_f32 v[114:115], v[114:115], v[122:123]
	v_cvt_pk_bf16_f32 v124, v116, v117
	v_cvt_pk_bf16_f32 v125, v118, v119
	v_cvt_pk_bf16_f32 v126, v112, v113
	v_cvt_pk_bf16_f32 v127, v114, v115
	global_store_dwordx4 v[176:177], v[124:127], off
	v_pk_mul_f32 v[100:101], v[108:109], v[100:101]
	v_pk_mul_f32 v[102:103], v[110:111], v[102:103]
	v_pk_mul_f32 v[96:97], v[104:105], v[96:97]
	v_pk_mul_f32 v[98:99], v[106:107], v[98:99]
	s_waitcnt lgkmcnt(6)
	v_mov_b32_e32 v150, v163
	v_pk_mul_f32 v[108:109], v[108:109], v[150:151] op_sel_hi:[1,0]
	v_pk_mul_f32 v[110:111], v[110:111], v[150:151] op_sel_hi:[1,0]
	v_pk_mul_f32 v[104:105], v[104:105], v[150:151] op_sel_hi:[1,0]
	v_pk_mul_f32 v[106:107], v[106:107], v[150:151] op_sel_hi:[1,0]
	v_exp_f32_e32 v108, v108
	v_exp_f32_e32 v109, v109
	v_exp_f32_e32 v110, v110
	v_exp_f32_e32 v111, v111
	v_exp_f32_e32 v104, v104
	v_exp_f32_e32 v105, v105
	v_exp_f32_e32 v106, v106
	v_exp_f32_e32 v107, v107
	v_fma_f32 v108, v108, v162, v162
	v_fma_f32 v109, v109, v162, v162
	v_fma_f32 v110, v110, v162, v162
	v_fma_f32 v111, v111, v162, v162
	v_fma_f32 v104, v104, v162, v162
	v_fma_f32 v105, v105, v162, v162
	v_fma_f32 v106, v106, v162, v162
	v_fma_f32 v107, v107, v162, v162
	v_rcp_f32_e32 v108, v108
	v_rcp_f32_e32 v109, v109
	v_rcp_f32_e32 v110, v110
	v_rcp_f32_e32 v111, v111
	v_rcp_f32_e32 v104, v104
	v_rcp_f32_e32 v105, v105
	v_rcp_f32_e32 v106, v106
	v_rcp_f32_e32 v107, v107
	s_mov_b32 s8, 0x16000
	v_pk_mul_f32 v[100:101], v[100:101], v[108:109]
	v_pk_mul_f32 v[102:103], v[102:103], v[110:111]
	v_pk_mul_f32 v[96:97], v[96:97], v[104:105]
	v_pk_mul_f32 v[98:99], v[98:99], v[106:107]
	v_cvt_pk_bf16_f32 v108, v100, v101
	v_cvt_pk_bf16_f32 v109, v102, v103
	v_cvt_pk_bf16_f32 v110, v96, v97
	v_cvt_pk_bf16_f32 v111, v98, v99
	v_lshl_add_u64 v[178:179], v[176:177], 0, s[8:9]
	global_store_dwordx4 v[178:179], v[108:111], off
	v_pk_mul_f32 v[84:85], v[92:93], v[84:85]
	v_pk_mul_f32 v[86:87], v[94:95], v[86:87]
	v_pk_mul_f32 v[80:81], v[88:89], v[80:81]
	v_pk_mul_f32 v[82:83], v[90:91], v[82:83]
	s_waitcnt lgkmcnt(5)
	v_mov_b32_e32 v150, v165
	v_pk_mul_f32 v[92:93], v[92:93], v[150:151] op_sel_hi:[1,0]
	v_pk_mul_f32 v[94:95], v[94:95], v[150:151] op_sel_hi:[1,0]
	v_pk_mul_f32 v[88:89], v[88:89], v[150:151] op_sel_hi:[1,0]
	v_pk_mul_f32 v[90:91], v[90:91], v[150:151] op_sel_hi:[1,0]
	v_exp_f32_e32 v92, v92
	v_exp_f32_e32 v93, v93
	v_exp_f32_e32 v94, v94
	v_exp_f32_e32 v95, v95
	v_exp_f32_e32 v88, v88
	v_exp_f32_e32 v89, v89
	v_exp_f32_e32 v90, v90
	v_exp_f32_e32 v91, v91
	v_fma_f32 v92, v92, v164, v164
	v_fma_f32 v93, v93, v164, v164
	v_fma_f32 v94, v94, v164, v164
	v_fma_f32 v95, v95, v164, v164
	v_fma_f32 v88, v88, v164, v164
	v_fma_f32 v89, v89, v164, v164
	v_fma_f32 v90, v90, v164, v164
	v_fma_f32 v91, v91, v164, v164
	v_rcp_f32_e32 v92, v92
	v_rcp_f32_e32 v93, v93
	v_rcp_f32_e32 v94, v94
	v_rcp_f32_e32 v95, v95
	v_rcp_f32_e32 v88, v88
	v_rcp_f32_e32 v89, v89
	v_rcp_f32_e32 v90, v90
	v_rcp_f32_e32 v91, v91
	s_mov_b32 s8, 0x2c000
	v_pk_mul_f32 v[84:85], v[84:85], v[92:93]
	v_pk_mul_f32 v[86:87], v[86:87], v[94:95]
	v_pk_mul_f32 v[80:81], v[80:81], v[88:89]
	v_pk_mul_f32 v[82:83], v[82:83], v[90:91]
	v_cvt_pk_bf16_f32 v92, v84, v85
	v_cvt_pk_bf16_f32 v93, v86, v87
	v_cvt_pk_bf16_f32 v94, v80, v81
	v_cvt_pk_bf16_f32 v95, v82, v83
	v_lshl_add_u64 v[178:179], v[176:177], 0, s[8:9]
	global_store_dwordx4 v[178:179], v[92:95], off
	v_pk_mul_f32 v[68:69], v[76:77], v[68:69]
	v_pk_mul_f32 v[70:71], v[78:79], v[70:71]
	v_pk_mul_f32 v[64:65], v[72:73], v[64:65]
	v_pk_mul_f32 v[66:67], v[74:75], v[66:67]
	s_waitcnt lgkmcnt(4)
; __device__ __forceinline__ unsigned cvtpk(float lo, float hi) { f32x2_t v = {lo, hi}; bf16x2_t b = __builtin_convertvector(v, bf16x2_t); return __builtin_bit_cast(unsigned, b); }
;     __device__ __forceinline__ void operator()(const f32x4 (&acc)[2][2][4][2], const Unit& u, int wr, int wc, int fr, int fq) const {
;     ...
;                 const int row = row0 + ai * HALF + m * 16;
;                 const float rs = 1.0f / sqrtf(ssq_sum(ssq + (size_t)row * 16) * (1.0f / DM) + EPS);
;                 float hv[8];
; #pragma unroll
;                 for (int n = 0; n < 2; ++n)
; #pragma unroll
;                     for (int e = 0; e < 4; ++e) {
;                         const float gg = acc[ai][0][m][n][e] * rs, uu = acc[ai][1][m][n][e] * rs;
;                         const float den = 1.0f + __builtin_amdgcn_exp2f(-gg * LOG2E);
;                         hv[n * 4 + e] = gg * uu * __builtin_amdgcn_rcpf(den);
;                     }
;                 u32x4 w; w.x = cvtpk(hv[0], hv[1]); w.y = cvtpk(hv[2], hv[3]); w.z = cvtpk(hv[4], hv[5]); w.w = cvtpk(hv[6], hv[7]);
;                 *(u32x4*)(H + (size_t)row * DFF + col0) = w;
	v_mov_b32_e32 v150, v167
	v_pk_mul_f32 v[76:77], v[76:77], v[150:151] op_sel_hi:[1,0]
	v_pk_mul_f32 v[78:79], v[78:79], v[150:151] op_sel_hi:[1,0]
	v_pk_mul_f32 v[72:73], v[72:73], v[150:151] op_sel_hi:[1,0]
	v_pk_mul_f32 v[74:75], v[74:75], v[150:151] op_sel_hi:[1,0]
	v_exp_f32_e32 v76, v76
	v_exp_f32_e32 v77, v77
	v_exp_f32_e32 v78, v78
	v_exp_f32_e32 v79, v79
	v_exp_f32_e32 v72, v72
	v_exp_f32_e32 v73, v73
	v_exp_f32_e32 v74, v74
	v_exp_f32_e32 v75, v75
	v_fma_f32 v76, v76, v166, v166
	v_fma_f32 v77, v77, v166, v166
	v_fma_f32 v78, v78, v166, v166
	v_fma_f32 v79, v79, v166, v166
	v_fma_f32 v72, v72, v166, v166
	v_fma_f32 v73, v73, v166, v166
	v_fma_f32 v74, v74, v166, v166
	v_fma_f32 v75, v75, v166, v166
	v_rcp_f32_e32 v76, v76
	v_rcp_f32_e32 v77, v77
	v_rcp_f32_e32 v78, v78
	v_rcp_f32_e32 v79, v79
	v_rcp_f32_e32 v72, v72
	v_rcp_f32_e32 v73, v73
	v_rcp_f32_e32 v74, v74
	v_rcp_f32_e32 v75, v75
	s_mov_b32 s8, 0x42000
	v_pk_mul_f32 v[68:69], v[68:69], v[76:77]
	v_pk_mul_f32 v[70:71], v[70:71], v[78:79]
	v_pk_mul_f32 v[64:65], v[64:65], v[72:73]
	v_pk_mul_f32 v[66:67], v[66:67], v[74:75]
	v_cvt_pk_bf16_f32 v76, v68, v69
	v_cvt_pk_bf16_f32 v77, v70, v71
	v_cvt_pk_bf16_f32 v78, v64, v65
	v_cvt_pk_bf16_f32 v79, v66, v67
	v_lshl_add_u64 v[178:179], v[176:177], 0, s[8:9]
	global_store_dwordx4 v[178:179], v[76:79], off
	v_pk_mul_f32 v[52:53], v[60:61], v[52:53]
	v_pk_mul_f32 v[54:55], v[62:63], v[54:55]
	v_pk_mul_f32 v[48:49], v[56:57], v[48:49]
	v_pk_mul_f32 v[50:51], v[58:59], v[50:51]
	s_waitcnt lgkmcnt(3)
	v_mov_b32_e32 v150, v169
	v_pk_mul_f32 v[60:61], v[60:61], v[150:151] op_sel_hi:[1,0]
	v_pk_mul_f32 v[62:63], v[62:63], v[150:151] op_sel_hi:[1,0]
	v_pk_mul_f32 v[56:57], v[56:57], v[150:151] op_sel_hi:[1,0]
	v_pk_mul_f32 v[58:59], v[58:59], v[150:151] op_sel_hi:[1,0]
	v_exp_f32_e32 v60, v60
	v_exp_f32_e32 v61, v61
	v_exp_f32_e32 v62, v62
	v_exp_f32_e32 v63, v63
	v_exp_f32_e32 v56, v56
	v_exp_f32_e32 v57, v57
	v_exp_f32_e32 v58, v58
	v_exp_f32_e32 v59, v59
	v_fma_f32 v60, v60, v168, v168
	v_fma_f32 v61, v61, v168, v168
	v_fma_f32 v62, v62, v168, v168
	v_fma_f32 v63, v63, v168, v168
	v_fma_f32 v56, v56, v168, v168
	v_fma_f32 v57, v57, v168, v168
	v_fma_f32 v58, v58, v168, v168
	v_fma_f32 v59, v59, v168, v168
	v_rcp_f32_e32 v60, v60
	v_rcp_f32_e32 v61, v61
	v_rcp_f32_e32 v62, v62
	v_rcp_f32_e32 v63, v63
	v_rcp_f32_e32 v56, v56
	v_rcp_f32_e32 v57, v57
	v_rcp_f32_e32 v58, v58
	v_rcp_f32_e32 v59, v59
	s_mov_b32 s8, 0xb0000
	v_pk_mul_f32 v[52:53], v[52:53], v[60:61]
	v_pk_mul_f32 v[54:55], v[54:55], v[62:63]
	v_pk_mul_f32 v[48:49], v[48:49], v[56:57]
	v_pk_mul_f32 v[50:51], v[50:51], v[58:59]
	v_cvt_pk_bf16_f32 v60, v52, v53
	v_cvt_pk_bf16_f32 v61, v54, v55
	v_cvt_pk_bf16_f32 v62, v48, v49
	v_cvt_pk_bf16_f32 v63, v50, v51
	v_lshl_add_u64 v[178:179], v[176:177], 0, s[8:9]
	global_store_dwordx4 v[178:179], v[60:63], off
	v_pk_mul_f32 v[36:37], v[44:45], v[36:37]
	v_pk_mul_f32 v[38:39], v[46:47], v[38:39]
	v_pk_mul_f32 v[32:33], v[40:41], v[32:33]
	v_pk_mul_f32 v[34:35], v[42:43], v[34:35]
	s_waitcnt lgkmcnt(2)
; __device__ __forceinline__ unsigned cvtpk(float lo, float hi) { f32x2_t v = {lo, hi}; bf16x2_t b = __builtin_convertvector(v, bf16x2_t); return __builtin_bit_cast(unsigned, b); }
; #define PG8_BAR __builtin_amdgcn_s_barrier()
; template <class Epi>
; __device__ __forceinline__ void gemm_phase(LAS unsigned char* lds, const Gemm g, const StaticOrder& S, const Epi& E, int wave_s) {
;     ...
;         cur = nxt; cA = nA; cB = nB; ++ui;
;         if (wr == 1) PG8_BAR;
;     __device__ __forceinline__ void operator()(const f32x4 (&acc)[2][2][4][2], const Unit& u, int wr, int wc, int fr, int fq) const {
;     ...
;                 const int row = row0 + ai * HALF + m * 16;
;                 const float rs = 1.0f / sqrtf(ssq_sum(ssq + (size_t)row * 16) * (1.0f / DM) + EPS);
;                 float hv[8];
; #pragma unroll
;                 for (int n = 0; n < 2; ++n)
; #pragma unroll
;                     for (int e = 0; e < 4; ++e) {
;                         const float gg = acc[ai][0][m][n][e] * rs, uu = acc[ai][1][m][n][e] * rs;
;                         const float den = 1.0f + __builtin_amdgcn_exp2f(-gg * LOG2E);
;                         hv[n * 4 + e] = gg * uu * __builtin_amdgcn_rcpf(den);
;                     }
;                 u32x4 w; w.x = cvtpk(hv[0], hv[1]); w.y = cvtpk(hv[2], hv[3]); w.z = cvtpk(hv[4], hv[5]); w.w = cvtpk(hv[6], hv[7]);
;                 *(u32x4*)(H + (size_t)row * DFF + col0) = w;
	v_mov_b32_e32 v150, v171
	v_pk_mul_f32 v[44:45], v[44:45], v[150:151] op_sel_hi:[1,0]
	v_pk_mul_f32 v[46:47], v[46:47], v[150:151] op_sel_hi:[1,0]
	v_pk_mul_f32 v[40:41], v[40:41], v[150:151] op_sel_hi:[1,0]
	v_pk_mul_f32 v[42:43], v[42:43], v[150:151] op_sel_hi:[1,0]
	v_exp_f32_e32 v44, v44
	v_exp_f32_e32 v45, v45
	v_exp_f32_e32 v46, v46
	v_exp_f32_e32 v47, v47
	v_exp_f32_e32 v40, v40
	v_exp_f32_e32 v41, v41
	v_exp_f32_e32 v42, v42
	v_exp_f32_e32 v43, v43
	v_fma_f32 v44, v44, v170, v170
	v_fma_f32 v45, v45, v170, v170
	v_fma_f32 v46, v46, v170, v170
	v_fma_f32 v47, v47, v170, v170
	v_fma_f32 v40, v40, v170, v170
	v_fma_f32 v41, v41, v170, v170
	v_fma_f32 v42, v42, v170, v170
	v_fma_f32 v43, v43, v170, v170
	v_rcp_f32_e32 v44, v44
	v_rcp_f32_e32 v45, v45
	v_rcp_f32_e32 v46, v46
	v_rcp_f32_e32 v47, v47
	v_rcp_f32_e32 v40, v40
	v_rcp_f32_e32 v41, v41
	v_rcp_f32_e32 v42, v42
	v_rcp_f32_e32 v43, v43
	s_mov_b32 s8, 0xc6000
	v_pk_mul_f32 v[36:37], v[36:37], v[44:45]
	v_pk_mul_f32 v[38:39], v[38:39], v[46:47]
	v_pk_mul_f32 v[32:33], v[32:33], v[40:41]
	v_pk_mul_f32 v[34:35], v[34:35], v[42:43]
	v_cvt_pk_bf16_f32 v44, v36, v37
	v_cvt_pk_bf16_f32 v45, v38, v39
	v_cvt_pk_bf16_f32 v46, v32, v33
	v_cvt_pk_bf16_f32 v47, v34, v35
	v_lshl_add_u64 v[178:179], v[176:177], 0, s[8:9]
	global_store_dwordx4 v[178:179], v[44:47], off
	v_pk_mul_f32 v[20:21], v[28:29], v[20:21]
	v_pk_mul_f32 v[22:23], v[30:31], v[22:23]
	v_pk_mul_f32 v[16:17], v[24:25], v[16:17]
	v_pk_mul_f32 v[18:19], v[26:27], v[18:19]
	s_waitcnt lgkmcnt(1)
	v_mov_b32_e32 v150, v173
	v_pk_mul_f32 v[28:29], v[28:29], v[150:151] op_sel_hi:[1,0]
	v_pk_mul_f32 v[30:31], v[30:31], v[150:151] op_sel_hi:[1,0]
	v_pk_mul_f32 v[24:25], v[24:25], v[150:151] op_sel_hi:[1,0]
	v_pk_mul_f32 v[26:27], v[26:27], v[150:151] op_sel_hi:[1,0]
	v_exp_f32_e32 v28, v28
	v_exp_f32_e32 v29, v29
	v_exp_f32_e32 v30, v30
	v_exp_f32_e32 v31, v31
	v_exp_f32_e32 v24, v24
	v_exp_f32_e32 v25, v25
	v_exp_f32_e32 v26, v26
	v_exp_f32_e32 v27, v27
	v_fma_f32 v28, v28, v172, v172
	v_fma_f32 v29, v29, v172, v172
	v_fma_f32 v30, v30, v172, v172
	v_fma_f32 v31, v31, v172, v172
	v_fma_f32 v24, v24, v172, v172
	v_fma_f32 v25, v25, v172, v172
	v_fma_f32 v26, v26, v172, v172
	v_fma_f32 v27, v27, v172, v172
	v_rcp_f32_e32 v28, v28
	v_rcp_f32_e32 v29, v29
	v_rcp_f32_e32 v30, v30
	v_rcp_f32_e32 v31, v31
	v_rcp_f32_e32 v24, v24
	v_rcp_f32_e32 v25, v25
	v_rcp_f32_e32 v26, v26
	v_rcp_f32_e32 v27, v27
	s_mov_b32 s8, 0xdc000
	v_pk_mul_f32 v[20:21], v[20:21], v[28:29]
	v_pk_mul_f32 v[22:23], v[22:23], v[30:31]
	v_pk_mul_f32 v[16:17], v[16:17], v[24:25]
	v_pk_mul_f32 v[18:19], v[18:19], v[26:27]
	v_cvt_pk_bf16_f32 v28, v20, v21
	v_cvt_pk_bf16_f32 v29, v22, v23
	v_cvt_pk_bf16_f32 v30, v16, v17
	v_cvt_pk_bf16_f32 v31, v18, v19
	v_lshl_add_u64 v[178:179], v[176:177], 0, s[8:9]
	global_store_dwordx4 v[178:179], v[28:31], off
	v_pk_mul_f32 v[4:5], v[12:13], v[4:5]
	v_pk_mul_f32 v[6:7], v[14:15], v[6:7]
	v_pk_mul_f32 v[0:1], v[8:9], v[0:1]
	v_pk_mul_f32 v[2:3], v[10:11], v[2:3]
	s_waitcnt lgkmcnt(0)
	v_mov_b32_e32 v150, v175
	v_pk_mul_f32 v[12:13], v[12:13], v[150:151] op_sel_hi:[1,0]
	v_pk_mul_f32 v[14:15], v[14:15], v[150:151] op_sel_hi:[1,0]
	v_pk_mul_f32 v[8:9], v[8:9], v[150:151] op_sel_hi:[1,0]
	v_pk_mul_f32 v[10:11], v[10:11], v[150:151] op_sel_hi:[1,0]
	v_exp_f32_e32 v12, v12
	v_exp_f32_e32 v13, v13
	v_exp_f32_e32 v14, v14
	v_exp_f32_e32 v15, v15
	v_exp_f32_e32 v8, v8
	v_exp_f32_e32 v9, v9
	v_exp_f32_e32 v10, v10
	v_exp_f32_e32 v11, v11
	v_fma_f32 v12, v12, v174, v174
	v_fma_f32 v13, v13, v174, v174
	v_fma_f32 v14, v14, v174, v174
	v_fma_f32 v15, v15, v174, v174
	v_fma_f32 v8, v8, v174, v174
	v_fma_f32 v9, v9, v174, v174
	v_fma_f32 v10, v10, v174, v174
	v_fma_f32 v11, v11, v174, v174
	v_rcp_f32_e32 v12, v12
	v_rcp_f32_e32 v13, v13
	v_rcp_f32_e32 v14, v14
	v_rcp_f32_e32 v15, v15
	v_rcp_f32_e32 v8, v8
	v_rcp_f32_e32 v9, v9
	v_rcp_f32_e32 v10, v10
	v_rcp_f32_e32 v11, v11
	s_mov_b32 s8, 0xf2000
	v_pk_mul_f32 v[4:5], v[4:5], v[12:13]
	v_pk_mul_f32 v[6:7], v[6:7], v[14:15]
	v_pk_mul_f32 v[0:1], v[0:1], v[8:9]
	v_pk_mul_f32 v[2:3], v[2:3], v[10:11]
	v_cvt_pk_bf16_f32 v12, v4, v5
	v_cvt_pk_bf16_f32 v13, v6, v7
	v_cvt_pk_bf16_f32 v14, v0, v1
	v_cvt_pk_bf16_f32 v15, v2, v3
	v_lshl_add_u64 v[178:179], v[176:177], 0, s[8:9]
	global_store_dwordx4 v[178:179], v[12:15], off
	s_andn2_b64 vcc, exec, s[6:7]
	s_mov_b64 s[6:7], -1
	s_cbranch_vccnz .LBB0_237
	s_andn2_b64 vcc, exec, s[12:13]
	s_cbranch_vccnz .LBB0_236
	s_barrier
	s_branch .LBB0_236

; __device__ __forceinline__ unsigned cvtpk(float lo, float hi) { f32x2_t v = {lo, hi}; bf16x2_t b = __builtin_convertvector(v, bf16x2_t); return __builtin_bit_cast(unsigned, b); }
; __device__ __forceinline__ float ssq_sum(const float* p) {
;     const f32x4 a = *(const f32x4*)p, b = *(const f32x4*)(p + 4), c = *(const f32x4*)(p + 8), d = *(const f32x4*)(p + 12);
;     return (((a[0] + a[1]) + (a[2] + a[3])) + ((b[0] + b[1]) + (b[2] + b[3]))) + (((c[0] + c[1]) + (c[2] + c[3])) + ((d[0] + d[1]) + (d[2] + d[3])));
;     __device__ __forceinline__ void operator()(const f32x4 (&acc)[2][2][4][2], const Unit& u, int wr, int wc, int fr, int fq) const {
;         const int row0 = u.pm * BM + wr * 64 + fr, col0 = u.pn * 128 + wc * 32 + 8 * fq;
; #pragma unroll
;         for (int ai = 0; ai < 2; ++ai)
; #pragma unroll
;             for (int m = 0; m < 4; ++m) {
;                 const int row = row0 + ai * HALF + m * 16;
;                 const float rs = 1.0f / sqrtf(ssq_sum(ssq + (size_t)row * 16) * (1.0f / DM) + EPS);
;                 float hv[8];
; #pragma unroll
;                 for (int n = 0; n < 2; ++n)
; #pragma unroll
;                     for (int e = 0; e < 4; ++e) {
;                         const float gg = acc[ai][0][m][n][e] * rs, uu = acc[ai][1][m][n][e] * rs;
;                         const float den = 1.0f + __builtin_amdgcn_exp2f(-gg * LOG2E);
;                         hv[n * 4 + e] = gg * uu * __builtin_amdgcn_rcpf(den);
;                     }
;                 u32x4 w; w.x = cvtpk(hv[0], hv[1]); w.y = cvtpk(hv[2], hv[3]); w.z = cvtpk(hv[4], hv[5]); w.w = cvtpk(hv[6], hv[7]);
;                 *(u32x4*)(H + (size_t)row * DFF + col0) = w;
.LBB0_1054:
	v_readlane_b32 s9, v254, 7
	v_mbcnt_lo_u32_b32 v144, -1, 0
	v_mbcnt_hi_u32_b32 v144, -1, v144
	v_lshrrev_b32_e32 v145, 1, v144
	v_lshl_add_u32 v145, s9, 5, v145
	v_and_b32_e32 v146, 1, v144
	v_lshl_add_u32 v148, s8, 8, v152
	v_mov_b64_e32 v[146:147], s[14:15]
	v_mad_i64_i32 v[176:177], s[8:9], v148, s51, v[146:147]
	v_lshl_or_b32 v150, s2, 7, v154
	v_mov_b32_e32 v151, 0
	v_lshlrev_b64 v[150:151], 1, v[150:151]
	v_lshl_add_u64 v[176:177], v[176:177], 0, v[150:151]
	v_lshlrev_b32_e32 v145, 3, v145
	v_add_u32_e32 v145, 0x20100, v145
	v_lshlrev_b32_e32 v146, 3, v152
	v_add_u32_e32 v146, 0x20100, v146
	s_mov_b32 s9, 0
	v_pk_add_f32 v[160:161], v[230:231], v[232:233]
	v_pk_add_f32 v[164:165], v[234:235], v[236:237]
	v_pk_add_f32 v[160:161], v[160:161], v[164:165]
	v_add_f32_e32 v160, v160, v161
	s_nop 1
	v_add_f32_dpp v160, v160, v160 quad_perm:[1,0,3,2] row_mask:0xf bank_mask:0xf
	v_fmamk_f32 v160, v160, 0x3a800000, v158
	v_rsq_f32_e32 v161, v160
	s_nop 0
	v_mul_f32_e32 v161, 0xbfb8aa3b, v161
	ds_write_b64 v145, v[160:161]
	s_waitcnt lgkmcnt(0)
	s_barrier
	ds_read_b64 v[160:161], v146 offset:0
	ds_read_b64 v[162:163], v146 offset:128
	ds_read_b64 v[164:165], v146 offset:256
	ds_read_b64 v[166:167], v146 offset:384
	ds_read_b64 v[168:169], v146 offset:1024
	ds_read_b64 v[170:171], v146 offset:1152
	ds_read_b64 v[172:173], v146 offset:1280
	ds_read_b64 v[174:175], v146 offset:1408
	v_pk_mul_f32 v[116:117], v[124:125], v[116:117]
	v_pk_mul_f32 v[118:119], v[126:127], v[118:119]
	v_pk_mul_f32 v[112:113], v[120:121], v[112:113]
	v_pk_mul_f32 v[114:115], v[122:123], v[114:115]
	s_waitcnt lgkmcnt(7)
	v_mov_b32_e32 v150, v161
	v_pk_mul_f32 v[124:125], v[124:125], v[150:151] op_sel_hi:[1,0]
	v_pk_mul_f32 v[126:127], v[126:127], v[150:151] op_sel_hi:[1,0]
	v_pk_mul_f32 v[120:121], v[120:121], v[150:151] op_sel_hi:[1,0]
	v_pk_mul_f32 v[122:123], v[122:123], v[150:151] op_sel_hi:[1,0]
	v_exp_f32_e32 v124, v124
	v_exp_f32_e32 v125, v125
	v_exp_f32_e32 v126, v126
	v_exp_f32_e32 v127, v127
	v_exp_f32_e32 v120, v120
	v_exp_f32_e32 v121, v121
	v_exp_f32_e32 v122, v122
	v_exp_f32_e32 v123, v123
	v_fma_f32 v124, v124, v160, v160
	v_fma_f32 v125, v125, v160, v160
	v_fma_f32 v126, v126, v160, v160
	v_fma_f32 v127, v127, v160, v160
	v_fma_f32 v120, v120, v160, v160
	v_fma_f32 v121, v121, v160, v160
	v_fma_f32 v122, v122, v160, v160
	v_fma_f32 v123, v123, v160, v160
	v_rcp_f32_e32 v124, v124
	v_rcp_f32_e32 v125, v125
	v_rcp_f32_e32 v126, v126
	v_rcp_f32_e32 v127, v127
	v_rcp_f32_e32 v120, v120
	v_rcp_f32_e32 v121, v121
	v_rcp_f32_e32 v122, v122
	v_rcp_f32_e32 v123, v123
	v_pk_mul_f32 v[116:117], v[116:117], v[124:125]
	v_pk_mul_f32 v[118:119], v[118:119], v[126:127]
	v_pk_mul_f32 v[112:113], v[112:113], v[120:121]
	v_pk_mul_f32 v[114:115], v[114:115], v[122:123]
	v_cvt_pk_bf16_f32 v124, v116, v117
	v_cvt_pk_bf16_f32 v125, v118, v119
	v_cvt_pk_bf16_f32 v126, v112, v113
	v_cvt_pk_bf16_f32 v127, v114, v115
	global_store_dwordx4 v[176:177], v[124:127], off
	v_pk_mul_f32 v[100:101], v[108:109], v[100:101]
	v_pk_mul_f32 v[102:103], v[110:111], v[102:103]
	v_pk_mul_f32 v[96:97], v[104:105], v[96:97]
	v_pk_mul_f32 v[98:99], v[106:107], v[98:99]
	s_waitcnt lgkmcnt(6)
	v_mov_b32_e32 v150, v163
	v_pk_mul_f32 v[108:109], v[108:109], v[150:151] op_sel_hi:[1,0]
	v_pk_mul_f32 v[110:111], v[110:111], v[150:151] op_sel_hi:[1,0]
	v_pk_mul_f32 v[104:105], v[104:105], v[150:151] op_sel_hi:[1,0]
	v_pk_mul_f32 v[106:107], v[106:107], v[150:151] op_sel_hi:[1,0]
	v_exp_f32_e32 v108, v108
	v_exp_f32_e32 v109, v109
	v_exp_f32_e32 v110, v110
	v_exp_f32_e32 v111, v111
	v_exp_f32_e32 v104, v104
	v_exp_f32_e32 v105, v105
	v_exp_f32_e32 v106, v106
	v_exp_f32_e32 v107, v107
	v_fma_f32 v108, v108, v162, v162
	v_fma_f32 v109, v109, v162, v162
	v_fma_f32 v110, v110, v162, v162
	v_fma_f32 v111, v111, v162, v162
	v_fma_f32 v104, v104, v162, v162
	v_fma_f32 v105, v105, v162, v162
	v_fma_f32 v106, v106, v162, v162
	v_fma_f32 v107, v107, v162, v162
	v_rcp_f32_e32 v108, v108
	v_rcp_f32_e32 v109, v109
	v_rcp_f32_e32 v110, v110
	v_rcp_f32_e32 v111, v111
	v_rcp_f32_e32 v104, v104
	v_rcp_f32_e32 v105, v105
	v_rcp_f32_e32 v106, v106
	v_rcp_f32_e32 v107, v107
	s_mov_b32 s8, 0x16000
	v_pk_mul_f32 v[100:101], v[100:101], v[108:109]
	v_pk_mul_f32 v[102:103], v[102:103], v[110:111]
	v_pk_mul_f32 v[96:97], v[96:97], v[104:105]
	v_pk_mul_f32 v[98:99], v[98:99], v[106:107]
	v_cvt_pk_bf16_f32 v108, v100, v101
	v_cvt_pk_bf16_f32 v109, v102, v103
	v_cvt_pk_bf16_f32 v110, v96, v97
	v_cvt_pk_bf16_f32 v111, v98, v99
	v_lshl_add_u64 v[178:179], v[176:177], 0, s[8:9]
	global_store_dwordx4 v[178:179], v[108:111], off
	v_pk_mul_f32 v[84:85], v[92:93], v[84:85]
	v_pk_mul_f32 v[86:87], v[94:95], v[86:87]
	v_pk_mul_f32 v[80:81], v[88:89], v[80:81]
	v_pk_mul_f32 v[82:83], v[90:91], v[82:83]
	s_waitcnt lgkmcnt(5)
	v_mov_b32_e32 v150, v165
	v_pk_mul_f32 v[92:93], v[92:93], v[150:151] op_sel_hi:[1,0]
	v_pk_mul_f32 v[94:95], v[94:95], v[150:151] op_sel_hi:[1,0]
	v_pk_mul_f32 v[88:89], v[88:89], v[150:151] op_sel_hi:[1,0]
	v_pk_mul_f32 v[90:91], v[90:91], v[150:151] op_sel_hi:[1,0]
	v_exp_f32_e32 v92, v92
	v_exp_f32_e32 v93, v93
	v_exp_f32_e32 v94, v94
	v_exp_f32_e32 v95, v95
	v_exp_f32_e32 v88, v88
	v_exp_f32_e32 v89, v89
	v_exp_f32_e32 v90, v90
	v_exp_f32_e32 v91, v91
	v_fma_f32 v92, v92, v164, v164
	v_fma_f32 v93, v93, v164, v164
	v_fma_f32 v94, v94, v164, v164
	v_fma_f32 v95, v95, v164, v164
	v_fma_f32 v88, v88, v164, v164
	v_fma_f32 v89, v89, v164, v164
	v_fma_f32 v90, v90, v164, v164
	v_fma_f32 v91, v91, v164, v164
	v_rcp_f32_e32 v92, v92
	v_rcp_f32_e32 v93, v93
	v_rcp_f32_e32 v94, v94
	v_rcp_f32_e32 v95, v95
	v_rcp_f32_e32 v88, v88
	v_rcp_f32_e32 v89, v89
	v_rcp_f32_e32 v90, v90
	v_rcp_f32_e32 v91, v91
	s_mov_b32 s8, 0x2c000
	v_pk_mul_f32 v[84:85], v[84:85], v[92:93]
	v_pk_mul_f32 v[86:87], v[86:87], v[94:95]
	v_pk_mul_f32 v[80:81], v[80:81], v[88:89]
	v_pk_mul_f32 v[82:83], v[82:83], v[90:91]
	v_cvt_pk_bf16_f32 v92, v84, v85
	v_cvt_pk_bf16_f32 v93, v86, v87
	v_cvt_pk_bf16_f32 v94, v80, v81
	v_cvt_pk_bf16_f32 v95, v82, v83
	v_lshl_add_u64 v[178:179], v[176:177], 0, s[8:9]
	global_store_dwordx4 v[178:179], v[92:95], off
	v_pk_mul_f32 v[68:69], v[76:77], v[68:69]
	v_pk_mul_f32 v[70:71], v[78:79], v[70:71]
	v_pk_mul_f32 v[64:65], v[72:73], v[64:65]
	v_pk_mul_f32 v[66:67], v[74:75], v[66:67]
	s_waitcnt lgkmcnt(4)
; __device__ __forceinline__ unsigned cvtpk(float lo, float hi) { f32x2_t v = {lo, hi}; bf16x2_t b = __builtin_convertvector(v, bf16x2_t); return __builtin_bit_cast(unsigned, b); }
;     __device__ __forceinline__ void operator()(const f32x4 (&acc)[2][2][4][2], const Unit& u, int wr, int wc, int fr, int fq) const {
;     ...
;                 const int row = row0 + ai * HALF + m * 16;
;                 const float rs = 1.0f / sqrtf(ssq_sum(ssq + (size_t)row * 16) * (1.0f / DM) + EPS);
;                 float hv[8];
; #pragma unroll
;                 for (int n = 0; n < 2; ++n)
; #pragma unroll
;                     for (int e = 0; e < 4; ++e) {
;                         const float gg = acc[ai][0][m][n][e] * rs, uu = acc[ai][1][m][n][e] * rs;
;                         const float den = 1.0f + __builtin_amdgcn_exp2f(-gg * LOG2E);
;                         hv[n * 4 + e] = gg * uu * __builtin_amdgcn_rcpf(den);
;                     }
;                 u32x4 w; w.x = cvtpk(hv[0], hv[1]); w.y = cvtpk(hv[2], hv[3]); w.z = cvtpk(hv[4], hv[5]); w.w = cvtpk(hv[6], hv[7]);
;                 *(u32x4*)(H + (size_t)row * DFF + col0) = w;
	v_mov_b32_e32 v150, v167
	v_pk_mul_f32 v[76:77], v[76:77], v[150:151] op_sel_hi:[1,0]
	v_pk_mul_f32 v[78:79], v[78:79], v[150:151] op_sel_hi:[1,0]
	v_pk_mul_f32 v[72:73], v[72:73], v[150:151] op_sel_hi:[1,0]
	v_pk_mul_f32 v[74:75], v[74:75], v[150:151] op_sel_hi:[1,0]
	v_exp_f32_e32 v76, v76
	v_exp_f32_e32 v77, v77
	v_exp_f32_e32 v78, v78
	v_exp_f32_e32 v79, v79
	v_exp_f32_e32 v72, v72
	v_exp_f32_e32 v73, v73
	v_exp_f32_e32 v74, v74
	v_exp_f32_e32 v75, v75
	v_fma_f32 v76, v76, v166, v166
	v_fma_f32 v77, v77, v166, v166
	v_fma_f32 v78, v78, v166, v166
	v_fma_f32 v79, v79, v166, v166
	v_fma_f32 v72, v72, v166, v166
	v_fma_f32 v73, v73, v166, v166
	v_fma_f32 v74, v74, v166, v166
	v_fma_f32 v75, v75, v166, v166
	v_rcp_f32_e32 v76, v76
	v_rcp_f32_e32 v77, v77
	v_rcp_f32_e32 v78, v78
	v_rcp_f32_e32 v79, v79
	v_rcp_f32_e32 v72, v72
	v_rcp_f32_e32 v73, v73
	v_rcp_f32_e32 v74, v74
	v_rcp_f32_e32 v75, v75
	s_mov_b32 s8, 0x42000
	v_pk_mul_f32 v[68:69], v[68:69], v[76:77]
	v_pk_mul_f32 v[70:71], v[70:71], v[78:79]
	v_pk_mul_f32 v[64:65], v[64:65], v[72:73]
	v_pk_mul_f32 v[66:67], v[66:67], v[74:75]
	v_cvt_pk_bf16_f32 v76, v68, v69
	v_cvt_pk_bf16_f32 v77, v70, v71
	v_cvt_pk_bf16_f32 v78, v64, v65
	v_cvt_pk_bf16_f32 v79, v66, v67
	v_lshl_add_u64 v[178:179], v[176:177], 0, s[8:9]
	global_store_dwordx4 v[178:179], v[76:79], off
	v_pk_mul_f32 v[52:53], v[60:61], v[52:53]
	v_pk_mul_f32 v[54:55], v[62:63], v[54:55]
	v_pk_mul_f32 v[48:49], v[56:57], v[48:49]
	v_pk_mul_f32 v[50:51], v[58:59], v[50:51]
	s_waitcnt lgkmcnt(3)
	v_mov_b32_e32 v150, v169
	v_pk_mul_f32 v[60:61], v[60:61], v[150:151] op_sel_hi:[1,0]
	v_pk_mul_f32 v[62:63], v[62:63], v[150:151] op_sel_hi:[1,0]
	v_pk_mul_f32 v[56:57], v[56:57], v[150:151] op_sel_hi:[1,0]
	v_pk_mul_f32 v[58:59], v[58:59], v[150:151] op_sel_hi:[1,0]
	v_exp_f32_e32 v60, v60
	v_exp_f32_e32 v61, v61
	v_exp_f32_e32 v62, v62
	v_exp_f32_e32 v63, v63
	v_exp_f32_e32 v56, v56
	v_exp_f32_e32 v57, v57
	v_exp_f32_e32 v58, v58
	v_exp_f32_e32 v59, v59
	v_fma_f32 v60, v60, v168, v168
	v_fma_f32 v61, v61, v168, v168
	v_fma_f32 v62, v62, v168, v168
	v_fma_f32 v63, v63, v168, v168
	v_fma_f32 v56, v56, v168, v168
	v_fma_f32 v57, v57, v168, v168
	v_fma_f32 v58, v58, v168, v168
	v_fma_f32 v59, v59, v168, v168
	v_rcp_f32_e32 v60, v60
	v_rcp_f32_e32 v61, v61
	v_rcp_f32_e32 v62, v62
	v_rcp_f32_e32 v63, v63
	v_rcp_f32_e32 v56, v56
	v_rcp_f32_e32 v57, v57
	v_rcp_f32_e32 v58, v58
	v_rcp_f32_e32 v59, v59
	s_mov_b32 s8, 0xb0000
	v_pk_mul_f32 v[52:53], v[52:53], v[60:61]
	v_pk_mul_f32 v[54:55], v[54:55], v[62:63]
	v_pk_mul_f32 v[48:49], v[48:49], v[56:57]
	v_pk_mul_f32 v[50:51], v[50:51], v[58:59]
	v_cvt_pk_bf16_f32 v60, v52, v53
	v_cvt_pk_bf16_f32 v61, v54, v55
	v_cvt_pk_bf16_f32 v62, v48, v49
	v_cvt_pk_bf16_f32 v63, v50, v51
	v_lshl_add_u64 v[178:179], v[176:177], 0, s[8:9]
	global_store_dwordx4 v[178:179], v[60:63], off
	v_pk_mul_f32 v[36:37], v[44:45], v[36:37]
	v_pk_mul_f32 v[38:39], v[46:47], v[38:39]
	v_pk_mul_f32 v[32:33], v[40:41], v[32:33]
	v_pk_mul_f32 v[34:35], v[42:43], v[34:35]
	s_waitcnt lgkmcnt(2)
; __device__ __forceinline__ unsigned cvtpk(float lo, float hi) { f32x2_t v = {lo, hi}; bf16x2_t b = __builtin_convertvector(v, bf16x2_t); return __builtin_bit_cast(unsigned, b); }
; #define PG8_BAR __builtin_amdgcn_s_barrier()
; template <class Epi>
; __device__ __forceinline__ void gemm_phase(LAS unsigned char* lds, const Gemm g, const StaticOrder& S, const Epi& E, int wave_s) {
;     ...
;         cur = nxt; cA = nA; cB = nB; ++ui;
;         if (wr == 1) PG8_BAR;
;     __device__ __forceinline__ void operator()(const f32x4 (&acc)[2][2][4][2], const Unit& u, int wr, int wc, int fr, int fq) const {
;     ...
;                 const int row = row0 + ai * HALF + m * 16;
;                 const float rs = 1.0f / sqrtf(ssq_sum(ssq + (size_t)row * 16) * (1.0f / DM) + EPS);
;                 float hv[8];
; #pragma unroll
;                 for (int n = 0; n < 2; ++n)
; #pragma unroll
;                     for (int e = 0; e < 4; ++e) {
;                         const float gg = acc[ai][0][m][n][e] * rs, uu = acc[ai][1][m][n][e] * rs;
;                         const float den = 1.0f + __builtin_amdgcn_exp2f(-gg * LOG2E);
;                         hv[n * 4 + e] = gg * uu * __builtin_amdgcn_rcpf(den);
;                     }
;                 u32x4 w; w.x = cvtpk(hv[0], hv[1]); w.y = cvtpk(hv[2], hv[3]); w.z = cvtpk(hv[4], hv[5]); w.w = cvtpk(hv[6], hv[7]);
;                 *(u32x4*)(H + (size_t)row * DFF + col0) = w;
	v_mov_b32_e32 v150, v171
	v_pk_mul_f32 v[44:45], v[44:45], v[150:151] op_sel_hi:[1,0]
	v_pk_mul_f32 v[46:47], v[46:47], v[150:151] op_sel_hi:[1,0]
	v_pk_mul_f32 v[40:41], v[40:41], v[150:151] op_sel_hi:[1,0]
	v_pk_mul_f32 v[42:43], v[42:43], v[150:151] op_sel_hi:[1,0]
	v_exp_f32_e32 v44, v44
	v_exp_f32_e32 v45, v45
	v_exp_f32_e32 v46, v46
	v_exp_f32_e32 v47, v47
	v_exp_f32_e32 v40, v40
	v_exp_f32_e32 v41, v41
	v_exp_f32_e32 v42, v42
	v_exp_f32_e32 v43, v43
	v_fma_f32 v44, v44, v170, v170
	v_fma_f32 v45, v45, v170, v170
	v_fma_f32 v46, v46, v170, v170
	v_fma_f32 v47, v47, v170, v170
	v_fma_f32 v40, v40, v170, v170
	v_fma_f32 v41, v41, v170, v170
	v_fma_f32 v42, v42, v170, v170
	v_fma_f32 v43, v43, v170, v170
	v_rcp_f32_e32 v44, v44
	v_rcp_f32_e32 v45, v45
	v_rcp_f32_e32 v46, v46
	v_rcp_f32_e32 v47, v47
	v_rcp_f32_e32 v40, v40
	v_rcp_f32_e32 v41, v41
	v_rcp_f32_e32 v42, v42
	v_rcp_f32_e32 v43, v43
	s_mov_b32 s8, 0xc6000
	v_pk_mul_f32 v[36:37], v[36:37], v[44:45]
	v_pk_mul_f32 v[38:39], v[38:39], v[46:47]
	v_pk_mul_f32 v[32:33], v[32:33], v[40:41]
	v_pk_mul_f32 v[34:35], v[34:35], v[42:43]
	v_cvt_pk_bf16_f32 v44, v36, v37
	v_cvt_pk_bf16_f32 v45, v38, v39
	v_cvt_pk_bf16_f32 v46, v32, v33
	v_cvt_pk_bf16_f32 v47, v34, v35
	v_lshl_add_u64 v[178:179], v[176:177], 0, s[8:9]
	global_store_dwordx4 v[178:179], v[44:47], off
	v_pk_mul_f32 v[20:21], v[28:29], v[20:21]
	v_pk_mul_f32 v[22:23], v[30:31], v[22:23]
	v_pk_mul_f32 v[16:17], v[24:25], v[16:17]
	v_pk_mul_f32 v[18:19], v[26:27], v[18:19]
	s_waitcnt lgkmcnt(1)
	v_mov_b32_e32 v150, v173
	v_pk_mul_f32 v[28:29], v[28:29], v[150:151] op_sel_hi:[1,0]
	v_pk_mul_f32 v[30:31], v[30:31], v[150:151] op_sel_hi:[1,0]
	v_pk_mul_f32 v[24:25], v[24:25], v[150:151] op_sel_hi:[1,0]
	v_pk_mul_f32 v[26:27], v[26:27], v[150:151] op_sel_hi:[1,0]
	v_exp_f32_e32 v28, v28
	v_exp_f32_e32 v29, v29
	v_exp_f32_e32 v30, v30
	v_exp_f32_e32 v31, v31
	v_exp_f32_e32 v24, v24
	v_exp_f32_e32 v25, v25
	v_exp_f32_e32 v26, v26
	v_exp_f32_e32 v27, v27
	v_fma_f32 v28, v28, v172, v172
	v_fma_f32 v29, v29, v172, v172
	v_fma_f32 v30, v30, v172, v172
	v_fma_f32 v31, v31, v172, v172
	v_fma_f32 v24, v24, v172, v172
	v_fma_f32 v25, v25, v172, v172
	v_fma_f32 v26, v26, v172, v172
	v_fma_f32 v27, v27, v172, v172
	v_rcp_f32_e32 v28, v28
	v_rcp_f32_e32 v29, v29
	v_rcp_f32_e32 v30, v30
	v_rcp_f32_e32 v31, v31
	v_rcp_f32_e32 v24, v24
	v_rcp_f32_e32 v25, v25
	v_rcp_f32_e32 v26, v26
	v_rcp_f32_e32 v27, v27
	s_mov_b32 s8, 0xdc000
	v_pk_mul_f32 v[20:21], v[20:21], v[28:29]
	v_pk_mul_f32 v[22:23], v[22:23], v[30:31]
	v_pk_mul_f32 v[16:17], v[16:17], v[24:25]
	v_pk_mul_f32 v[18:19], v[18:19], v[26:27]
	v_cvt_pk_bf16_f32 v28, v20, v21
	v_cvt_pk_bf16_f32 v29, v22, v23
	v_cvt_pk_bf16_f32 v30, v16, v17
	v_cvt_pk_bf16_f32 v31, v18, v19
	v_lshl_add_u64 v[178:179], v[176:177], 0, s[8:9]
	global_store_dwordx4 v[178:179], v[28:31], off
	v_pk_mul_f32 v[4:5], v[12:13], v[4:5]
	v_pk_mul_f32 v[6:7], v[14:15], v[6:7]
	v_pk_mul_f32 v[0:1], v[8:9], v[0:1]
	v_pk_mul_f32 v[2:3], v[10:11], v[2:3]
	s_waitcnt lgkmcnt(0)
	v_mov_b32_e32 v150, v175
	v_pk_mul_f32 v[12:13], v[12:13], v[150:151] op_sel_hi:[1,0]
	v_pk_mul_f32 v[14:15], v[14:15], v[150:151] op_sel_hi:[1,0]
	v_pk_mul_f32 v[8:9], v[8:9], v[150:151] op_sel_hi:[1,0]
	v_pk_mul_f32 v[10:11], v[10:11], v[150:151] op_sel_hi:[1,0]
	v_exp_f32_e32 v12, v12
	v_exp_f32_e32 v13, v13
	v_exp_f32_e32 v14, v14
	v_exp_f32_e32 v15, v15
	v_exp_f32_e32 v8, v8
	v_exp_f32_e32 v9, v9
	v_exp_f32_e32 v10, v10
	v_exp_f32_e32 v11, v11
	v_fma_f32 v12, v12, v174, v174
	v_fma_f32 v13, v13, v174, v174
	v_fma_f32 v14, v14, v174, v174
	v_fma_f32 v15, v15, v174, v174
	v_fma_f32 v8, v8, v174, v174
	v_fma_f32 v9, v9, v174, v174
	v_fma_f32 v10, v10, v174, v174
	v_fma_f32 v11, v11, v174, v174
	v_rcp_f32_e32 v12, v12
	v_rcp_f32_e32 v13, v13
	v_rcp_f32_e32 v14, v14
	v_rcp_f32_e32 v15, v15
	v_rcp_f32_e32 v8, v8
	v_rcp_f32_e32 v9, v9
	v_rcp_f32_e32 v10, v10
	v_rcp_f32_e32 v11, v11
	s_mov_b32 s8, 0xf2000
	v_pk_mul_f32 v[4:5], v[4:5], v[12:13]
	v_pk_mul_f32 v[6:7], v[6:7], v[14:15]
	v_pk_mul_f32 v[0:1], v[0:1], v[8:9]
	v_pk_mul_f32 v[2:3], v[2:3], v[10:11]
	v_cvt_pk_bf16_f32 v12, v4, v5
	v_cvt_pk_bf16_f32 v13, v6, v7
	v_cvt_pk_bf16_f32 v14, v0, v1
	v_cvt_pk_bf16_f32 v15, v2, v3
	v_lshl_add_u64 v[178:179], v[176:177], 0, s[8:9]
	global_store_dwordx4 v[178:179], v[12:15], off
	s_andn2_b64 vcc, exec, s[6:7]
	s_mov_b64 s[6:7], -1
	s_cbranch_vccnz .LBB0_1047
	s_andn2_b64 vcc, exec, s[12:13]
	s_cbranch_vccnz .LBB0_1046
	s_barrier
	s_branch .LBB0_1046
